# dead zero-initialisations removed from the MoBA item prologue
# baseline (speedup 1.0000x reference)
; #define LAS __attribute__((address_space(3)))
; template <bool CAUSAL> __device__ __forceinline__ void moba_span(lbyte* kbuf, lbyte* vbuf, const bf16* Kh, const bf16* Vh, int kpos0, int nsub, const s16x8* qf, int tq, bool valid, int qlo, int qhi, ...
;     Sub32 st; sub_load(st, Kh + (size_t)kpos0 * 64, Vh + (size_t)kpos0 * 64, lane);
; #pragma unroll 1
;     for (int su = 0; su < nsub; ++su) {
;         const int key0 = kpos0 + 32 * su;
;         sub_write(st, kbuf, vbuf, lane);
;         if (su + 1 < nsub) sub_load(st, Kh + (size_t)(key0 + 32) * 64, Vh + (size_t)(key0 + 32) * 64, lane);
; __device__ __forceinline__ void moba_unit2(lbyte* lds, const bf16* QKV, bf16* AO, unsigned char* part, unsigned char* part3, const float* km2, const float* rel_bias, int b, int hm, int own) {
;     ...
;         unsigned it = 0u; if (lane == 0) it = __hip_atomic_fetch_add(ctr, 1u, __ATOMIC_RELAXED, __HIP_MEMORY_SCOPE_WORKGROUP);
;         it = (unsigned)__builtin_amdgcn_readfirstlane((int)it);
;         if (it >= total) break;
;         const int n = __builtin_amdgcn_readfirstlane((int)itemn[it]);
;         const int c = (int)(it - istart[n]), idx = 32 * c + l31; const bool valid = idx < (int)cnt[n];
;         const unsigned ent = list[n * 256 + (valid ? idx : 32 * c)]; const int qid = ent & 255, slot = ent >> 8, tq = own * 256 + qid;
;         s16x8 qf[4];
; #pragma unroll
;         for (int cc = 0; cc < 4; ++cc) qf[cc] = *(const LAS s16x8*)(lds + MC_Q + qid * KP64 + (16 * cc + 8 * h) * 2);
;         f32x16 o[2];
; #pragma unroll
;         for (int r = 0; r < 16; ++r) { o[0][r] = 0.f; o[1][r] = 0.f; }
;         float m = -1e30f, l = 0.f;
;         moba_span<false>(kbuf, vbuf, Kh, Vh, 256 * n, 8, qf, tq, valid, own * 256, own * 256 + 255, dtab, tab, thr, m, l, o, lane, l31, h);
.LBB0_663:
	s_or_b64 exec, exec, s[8:9]
	v_readfirstlane_b32 s11, v0
	s_mov_b64 s[8:9], -1
	s_waitcnt lgkmcnt(0)
	v_cmp_ge_u32_e32 vcc, s11, v240
	s_cbranch_vccnz .LBB0_658
	s_add_i32 s8, s11, 0
	s_add_i32 s8, s8, 0x1b000
	v_mov_b32_e32 v0, s8
	ds_read_u8 v0, v0
	v_mov_b32_e32 v6, v1
	v_mov_b32_e32 v7, v1
	v_mov_b32_e32 v8, v1
	v_mov_b32_e32 v9, v1
	s_waitcnt lgkmcnt(0)
	v_readfirstlane_b32 s8, v0
	s_lshl_b32 s9, s8, 2
	s_add_i32 s9, s9, 0
	s_add_i32 s14, s9, 0x21080
	v_mov_b32_e32 v0, s14
	ds_read_b32 v0, v0
	s_add_i32 s9, s9, 0x21000
	v_mov_b32_e32 v2, s9
	ds_read_b32 v2, v2
	s_lshl_b32 s22, s8, 8
	s_waitcnt lgkmcnt(1)
	v_sub_u32_e32 v0, s11, v0
	v_lshlrev_b32_e32 v0, 5, v0
	s_lshl_b32 s8, s8, 9
	v_or_b32_e32 v3, v0, v183
	s_add_i32 s14, s8, 0
	s_waitcnt lgkmcnt(0)
	v_cmp_lt_i32_e64 s[8:9], v3, v2
	s_ashr_i32 s23, s22, 31
	v_mov_b32_e32 v10, v1
	v_cndmask_b32_e64 v0, v0, v3, s[8:9]
	v_lshl_add_u32 v0, v0, 1, s14
	s_lshl_b64 s[14:15], s[22:23], 7
	v_add_u32_e32 v0, 0x1d000, v0
	v_lshl_add_u64 v[2:3], v[190:191], 0, s[14:15]
	ds_read_u16 v236, v0
	v_lshl_add_u64 v[4:5], v[192:193], 0, s[14:15]
	global_load_dwordx4 v[98:101], v[2:3], off
	global_load_dwordx4 v[106:109], v[2:3], off offset:1024
	global_load_dwordx4 v[122:125], v[4:5], off
	global_load_dwordx4 v[126:129], v[4:5], off offset:1024
	global_load_dwordx4 v[130:133], v[2:3], off offset:2048
	global_load_dwordx4 v[134:137], v[2:3], off offset:3072
	global_load_dwordx4 v[138:141], v[4:5], off offset:2048
	global_load_dwordx4 v[142:145], v[4:5], off offset:3072
	v_mov_b32_e32 v2, v1
	v_mov_b32_e32 v3, v1
	s_waitcnt lgkmcnt(0)
	v_and_b32_e32 v234, 0xff, v236
	v_mad_u32_u24 v0, v234, s73, v242
	ds_read_b128 v[102:105], v0
	ds_read_b128 v[110:113], v0 offset:32
	ds_read_b128 v[114:117], v0 offset:64
	ds_read_b128 v[118:121], v0 offset:96
	v_mov_b32_e32 v0, 0x3e38aa3b
	v_cndmask_b32_e64 v196, 0, v0, s[8:9]
	v_add_u32_e32 v0, s20, v234
	v_subrev_u32_e32 v235, s22, v0
	v_add_u32_e32 v0, v250, v234
	v_mov_b32_e32 v4, v1
	v_mov_b32_e32 v5, v1
	v_mov_b32_e32 v11, v1
	v_mov_b32_e32 v12, v1
	v_mov_b32_e32 v13, v1
	v_mov_b32_e32 v14, v1
	v_mov_b32_e32 v15, v1
	v_mov_b32_e32 v16, v1
	v_mov_b32_e32 v17, v1
	v_mov_b32_e32 v18, v1
	v_mov_b32_e32 v19, v1
	v_mov_b32_e32 v20, v1
	v_mov_b32_e32 v21, v1
	v_mov_b32_e32 v22, v1
	v_mov_b32_e32 v23, v1
	v_mov_b32_e32 v24, v1
	v_mov_b32_e32 v25, v1
	v_mov_b32_e32 v26, v1
	v_mov_b32_e32 v27, v1
	v_mov_b32_e32 v28, v1
	v_mov_b32_e32 v29, v1
	v_mov_b32_e32 v30, v1
	v_mov_b32_e32 v31, v1
	v_subrev_u32_e32 v237, s22, v0
	v_mov_b32_e32 v0, v1
	v_mov_b32_e32 v195, 0
	v_mov_b64_e32 v[32:33], v[30:31]
	s_mov_b32 s11, 0
	v_mov_b32_e32 v197, v196
	s_sub_i32 s14, s20, s22
	s_or_b32 s22, s22, 32
	v_mov_b32_e32 v231, 0xf149f2ca
	v_mov_b64_e32 v[30:31], v[28:29]
	v_mov_b64_e32 v[28:29], v[26:27]
	v_mov_b64_e32 v[26:27], v[24:25]
	v_mov_b64_e32 v[24:25], v[22:23]
	v_mov_b64_e32 v[22:23], v[20:21]
	v_mov_b64_e32 v[20:21], v[18:19]
	v_mov_b64_e32 v[18:19], v[16:17]
	v_mov_b64_e32 v[16:17], v[14:15]
	v_mov_b64_e32 v[14:15], v[12:13]
	v_mov_b64_e32 v[12:13], v[10:11]
	v_mov_b64_e32 v[10:11], v[8:9]
	v_mov_b64_e32 v[8:9], v[6:7]
	v_mov_b64_e32 v[6:7], v[4:5]
	v_mov_b64_e32 v[4:5], v[2:3]
	v_mov_b64_e32 v[2:3], v[0:1]
.LBB0_665:
	s_cmpk_eq_i32 s11, 0xff20
	s_waitcnt vmcnt(0)
	ds_write_b128 v251, v[98:101] offset:36864
	ds_write_b128 v251, v[122:125] offset:41472
	ds_write_b128 v251, v[106:109] offset:38016
	ds_write_b128 v251, v[126:129] offset:42624
	ds_write_b128 v251, v[130:133] offset:39168
	ds_write_b128 v251, v[138:141] offset:43776
	ds_write_b128 v251, v[134:137] offset:40320
	ds_write_b128 v251, v[142:145] offset:44928
	s_cbranch_scc1 .LBB0_667
	s_ashr_i32 s23, s22, 31
	s_lshl_b64 s[24:25], s[22:23], 7
	v_lshl_add_u64 v[34:35], v[190:191], 0, s[24:25]
	v_lshl_add_u64 v[36:37], v[192:193], 0, s[24:25]
	global_load_dwordx4 v[98:101], v[34:35], off
	global_load_dwordx4 v[106:109], v[34:35], off offset:1024
	global_load_dwordx4 v[122:125], v[36:37], off
	global_load_dwordx4 v[126:129], v[36:37], off offset:1024
	global_load_dwordx4 v[130:133], v[34:35], off offset:2048
	global_load_dwordx4 v[134:137], v[34:35], off offset:3072
	global_load_dwordx4 v[138:141], v[36:37], off offset:2048
	global_load_dwordx4 v[142:145], v[36:37], off offset:3072
